# GEMM phase pipeline fill de-serialised: K-step 1's six staging loads are issued before the wait+barrier that publishes K-step 0 (all six GEMM instances)
# speedup vs baseline: 1.0019x; 1.0019x over previous
; #define PG8_STAGE(bufoff, gbase, voff) do { _Pragma("unroll") for (int _i = 0; _i < 2; ++_i) \
;         __builtin_amdgcn_global_load_lds((const unsigned*)((const char*)(gbase) + (voff)[_i]), (PG8_LAS unsigned*)(lds + (bufoff) + ldsw + _i * 8192), 16, 0, 0); } while (0)
; #define PG8_WAIT_V(n) asm volatile("s_waitcnt vmcnt(" #n ")" ::: "memory")
; #define PG8_BAR __builtin_amdgcn_s_barrier()
;     __device__ __forceinline__ void operator()(const f32x4 (&acc)[2][2][4][2], const Unit& u, int wr, int wc, int fr, int fq, PG8_LAS unsigned char* lds, int tid, int quad = -1) const {
;     ...
;         const int rl0 = wr * 64 + fr; const int col0 = u.pn * BM + wc * 32 + 8 * fq;
; #pragma unroll
;         for (int ai = 0; ai < 2; ++ai)
; #pragma unroll
;             for (int m = 0; m < 4; ++m) {
;                 if (quad >= 0 && ai * 2 + (m >> 1) != quad) continue;
;                 const int rl = rl0 + ai * HALF + m * 16;
;                 const float sc = RS[rl];
; template <class Epi, class Sched, bool ALIGN_EPI = false, bool SP2 = false>
; __device__ __forceinline__ void gemm_phase(PG8_LAS unsigned char* lds, const Gemm g, const Sched& S, const Epi& E) {
;     ...
;     if constexpr (SP2) {
;         PG8_STAGE(PG8_SB(0, 0), cB, voffB); PG8_STAGE(PG8_SB(0, 1), cB + hstep, voffB); PG8_STAGE(PG8_SA(0, 0), cA, voffA); PG8_STAGE(PG8_SA(0, 1), cA + hstep, voffA);
;         if (wr == 1) PG8_BAR;
;         PG8_WAIT_V(2); PG8_BAR;
;         PG8_STAGE(PG8_SB(1, 0), cB + kstep, voffB); PG8_STAGE(PG8_SA(1, 0), cA + kstep, voffA); PG8_STAGE(PG8_SB(1, 1), cB + hstep + kstep, voffB);
;         PG8_WAIT_V(6); PG8_BAR;
;     } else {
;         PG8_STAGE(PG8_SB(0, 0), cB, voffB); PG8_STAGE(PG8_SA(0, 0), cA, voffA); PG8_STAGE(PG8_SB(0, 1), cB + hstep, voffB); PG8_STAGE(PG8_SA(0, 1), cA + hstep, voffA);
;         if (wr == 1) PG8_BAR;
;         PG8_WAIT_V(4); PG8_BAR;
;         PG8_STAGE(PG8_SB(1, 0), cB + kstep, voffB); PG8_STAGE(PG8_SA(1, 0), cA + kstep, voffA); PG8_STAGE(PG8_SB(1, 1), cB + hstep + kstep, voffB);
;         PG8_WAIT_V(6); PG8_BAR;
;     }
.LBB0_140:
	v_readlane_b32 s24, v255, 6
	s_lshl_b32 s11, s11, 5
	v_mov_b32_e32 v135, v1
	v_readlane_b32 s25, v255, 7
	s_and_b32 s21, s11, 0x60
	s_add_i32 m0, s1, 0x18000
	v_lshl_add_u64 v[2:3], v[2:3], 0, s[56:57]
	v_lshl_add_u64 v[14:15], s[24:25], 0, v[134:135]
	v_mov_b32_e32 v133, v1
	s_lshl_b32 s20, s17, 13
	s_lshl_b32 s22, s21, 7
	global_load_lds_dwordx4 v[2:3], off
	v_lshl_add_u64 v[2:3], v[4:5], 0, s[56:57]
	s_add_i32 m0, s1, 0x1a000
	s_add_i32 s11, s1, 0x8000
	s_add_i32 s26, s1, 0xa000
	v_lshl_add_u64 v[16:17], s[24:25], 0, v[132:133]
	global_load_lds_dwordx4 v[2:3], off
	v_lshl_add_u64 v[2:3], v[14:15], 0, s[56:57]
	s_mov_b32 m0, s11
	s_add_u32 s18, s44, 0x80080
	global_load_lds_dwordx4 v[2:3], off
	v_lshl_add_u64 v[2:3], v[16:17], 0, s[56:57]
	s_mov_b32 m0, s26
	s_addc_u32 s19, s45, 0
	global_load_lds_dwordx4 v[2:3], off
	s_add_i32 m0, s1, 0x1c000
	v_lshl_add_u64 v[2:3], s[18:19], 0, v[0:1]
	global_load_lds_dwordx4 v[2:3], off
	v_lshl_add_u64 v[2:3], s[18:19], 0, v[130:131]
	s_add_i32 m0, s1, 0x1e000
	v_lshlrev_b32_e32 v13, 2, v8
	global_load_lds_dwordx4 v[2:3], off
	s_waitcnt vmcnt(8)
	s_barrier
	v_lshrrev_b32_e32 v3, 1, v8
	v_and_b32_e32 v2, 15, v8
	v_and_b32_e32 v4, 24, v3
	v_lshl_or_b32 v146, s17, 6, v2
	v_lshlrev_b32_e32 v3, 1, v4
	v_lshl_or_b32 v2, v2, 6, v3
	v_lshlrev_b32_e32 v3, 2, v146
	v_and_b32_e32 v5, 32, v3
	v_and_b32_e32 v13, 32, v13
	v_bitop3_b32 v5, v2, s20, v5 bitop3:0xde
	v_bitop3_b32 v147, v2, s22, v13 bitop3:0xde
	v_and_b32_e32 v2, 1, v8
	v_cmp_eq_u32_e64 s[38:39], 0, v2
	v_add_u32_e32 v150, s30, v3
	v_lshlrev_b32_e32 v2, 6, v2
	v_mov_b32_e32 v3, v1
	v_lshl_add_u64 v[136:137], s[70:71], 0, v[2:3]
	v_lshlrev_b32_e32 v2, 15, v11
	v_and_b32_e32 v2, 0xffff0000, v2
	v_lshl_add_u32 v2, v10, 12, v2
	v_and_b32_e32 v3, 1, v11
	v_lshl_or_b32 v2, v3, 6, v2
	v_lshl_add_u32 v138, v12, 1, v2
	v_lshlrev_b32_e32 v2, 15, v6
	v_and_b32_e32 v2, 0xffff0000, v2
	s_waitcnt vmcnt(6)
	v_lshl_add_u32 v2, v7, 12, v2
	v_and_b32_e32 v3, 1, v6
	s_cmpk_lt_u32 s16, 0x100
	v_ashrrev_i32_e32 v148, 1, v8
	v_or_b32_e32 v151, 16, v146
	v_or_b32_e32 v153, 32, v146
	v_or_b32_e32 v155, 48, v146
	v_add_u32_e32 v157, 0x80, v146
	v_add_u32_e32 v159, 0x90, v146
	v_add_u32_e32 v161, 0xa0, v146
	v_add_u32_e32 v163, 0xb0, v146
	v_lshl_or_b32 v2, v3, 6, v2
	v_readlane_b32 s18, v255, 4
	s_cselect_b64 s[16:17], -1, 0
	s_mov_b32 s27, 0
	v_lshl_add_u32 v149, v148, 2, s30
	v_lshl_add_u32 v152, v151, 2, s30
	v_lshl_add_u32 v154, v153, 2, s30
	v_lshl_add_u32 v156, v155, 2, s30
	v_lshl_add_u32 v158, v157, 2, s30
	v_lshl_add_u32 v160, v159, 2, s30
	v_lshl_add_u32 v162, v161, 2, s30
	v_lshl_add_u32 v164, v163, 2, s30
	v_or_b32_e32 v165, s21, v4
	v_mov_b32_e32 v139, v1
	v_lshl_add_u32 v140, v9, 1, v2
	v_mov_b32_e32 v141, v1
	v_add_u32_e32 v166, 0, v5
	v_readlane_b32 s33, v255, 13
	s_mov_b32 s37, s18
	s_barrier
	v_readlane_b32 s19, v255, 5
	s_branch .LBB0_143

; #define PG8_STAGE(bufoff, gbase, voff) do { _Pragma("unroll") for (int _i = 0; _i < 2; ++_i) \
;         __builtin_amdgcn_global_load_lds((const unsigned*)((const char*)(gbase) + (voff)[_i]), (PG8_LAS unsigned*)(lds + (bufoff) + ldsw + _i * 8192), 16, 0, 0); } while (0)
; #define PG8_WAIT_V(n) asm volatile("s_waitcnt vmcnt(" #n ")" ::: "memory")
; #define PG8_BAR __builtin_amdgcn_s_barrier()
;     __device__ __forceinline__ void operator()(const f32x4 (&acc)[2][2][4][2], const Unit& u, int wr, int wc, int fr, int fq, PG8_LAS unsigned char* lds, int tid, int quad = -1) const {
;         const int row0 = u.pm * BM + wr * 64 + fr; const int col0 = u.pn * BM + wc * 32 + 8 * fq;
;         const int b0_ = row0 / LTOK, t0_ = row0 % LTOK; (void)b0_; (void)t0_;
; template <class Epi, class Sched, bool ALIGN_EPI = false, bool SP2 = false>
; __device__ __forceinline__ void gemm_phase(PG8_LAS unsigned char* lds, const Gemm g, const Sched& S, const Epi& E) {
;     ...
;     if constexpr (SP2) {
;         PG8_STAGE(PG8_SB(0, 0), cB, voffB); PG8_STAGE(PG8_SB(0, 1), cB + hstep, voffB); PG8_STAGE(PG8_SA(0, 0), cA, voffA); PG8_STAGE(PG8_SA(0, 1), cA + hstep, voffA);
;         if (wr == 1) PG8_BAR;
;         PG8_WAIT_V(2); PG8_BAR;
;         PG8_STAGE(PG8_SB(1, 0), cB + kstep, voffB); PG8_STAGE(PG8_SA(1, 0), cA + kstep, voffA); PG8_STAGE(PG8_SB(1, 1), cB + hstep + kstep, voffB);
;         PG8_WAIT_V(6); PG8_BAR;
;     } else {
;         PG8_STAGE(PG8_SB(0, 0), cB, voffB); PG8_STAGE(PG8_SA(0, 0), cA, voffA); PG8_STAGE(PG8_SB(0, 1), cB + hstep, voffB); PG8_STAGE(PG8_SA(0, 1), cA + hstep, voffA);
;         if (wr == 1) PG8_BAR;
;         PG8_WAIT_V(4); PG8_BAR;
;         PG8_STAGE(PG8_SB(1, 0), cB + kstep, voffB); PG8_STAGE(PG8_SA(1, 0), cA + kstep, voffA); PG8_STAGE(PG8_SB(1, 1), cB + hstep + kstep, voffB);
;         PG8_WAIT_V(6); PG8_BAR;
;     }
.LBB0_483:
	v_bfe_u32 v18, v8, 4, 2
	v_and_b32_e32 v9, 15, v8
	v_lshlrev_b32_e32 v20, 4, v18
	v_lshlrev_b32_e32 v8, 2, v8
	s_and_b32 s37, s19, 3
	v_lshl_or_b32 v162, s20, 6, v9
	v_lshl_or_b32 v9, v9, 6, v20
	s_lshl_b32 s15, s20, 13
	v_and_b32_e32 v8, 32, v8
	v_lshl_add_u64 v[10:11], s[50:51], 0, v[0:1]
	v_mov_b32_e32 v147, v1
	v_bitop3_b32 v20, v9, s15, v8 bitop3:0xde
	s_lshl_b32 s15, s37, 12
	v_lshl_add_u64 v[12:13], s[50:51], 0, v[146:147]
	v_mov_b32_e32 v143, v1
	v_bitop3_b32 v163, v9, s15, v8 bitop3:0xde
	s_add_i32 m0, s3, 0x18000
	v_lshl_add_u64 v[8:9], v[10:11], 0, s[56:57]
	v_lshl_add_u64 v[14:15], s[24:25], 0, v[142:143]
	v_mov_b32_e32 v145, v1
	global_load_lds_dwordx4 v[8:9], off
	v_lshl_add_u64 v[8:9], v[12:13], 0, s[56:57]
	s_add_i32 m0, s3, 0x1a000
	s_add_i32 s49, s3, 0x8000
	s_add_i32 s54, s3, 0xa000
	v_lshl_add_u64 v[16:17], s[24:25], 0, v[144:145]
	global_load_lds_dwordx4 v[8:9], off
	v_lshl_add_u64 v[8:9], v[14:15], 0, s[56:57]
	s_mov_b32 m0, s49
	s_add_u32 s20, s50, 0x80080
	global_load_lds_dwordx4 v[8:9], off
	v_lshl_add_u64 v[8:9], v[16:17], 0, s[56:57]
	s_mov_b32 m0, s54
	s_addc_u32 s21, s51, 0
	global_load_lds_dwordx4 v[8:9], off
	s_add_i32 m0, s3, 0x1c000
	v_lshl_add_u64 v[8:9], s[20:21], 0, v[0:1]
	global_load_lds_dwordx4 v[8:9], off
	v_lshl_add_u64 v[8:9], s[20:21], 0, v[146:147]
	s_add_i32 m0, s3, 0x1e000
	v_lshlrev_b32_e32 v19, 3, v18
	global_load_lds_dwordx4 v[8:9], off
	s_waitcnt vmcnt(8)
	s_barrier
	v_lshlrev_b32_e32 v8, 15, v2
	v_and_b32_e32 v8, 0xffff0000, v8
	v_lshl_add_u32 v3, v3, 12, v8
	v_and_b32_e32 v2, 1, v2
	v_lshl_or_b32 v2, v2, 6, v3
	v_lshl_add_u32 v148, v4, 1, v2
	v_lshlrev_b32_e32 v2, 15, v5
	v_and_b32_e32 v2, 0xffff0000, v2
	s_waitcnt vmcnt(6)
	v_lshl_add_u32 v2, v6, 12, v2
	v_and_b32_e32 v3, 1, v5
	s_cmpk_lt_u32 s18, 0x100
	v_lshl_or_b32 v2, v3, 6, v2
	v_lshl_or_b32 v164, s37, 5, v19
	s_cselect_b64 s[18:19], -1, 0
	s_mov_b32 s55, 0
	v_cmp_eq_u32_e64 s[40:41], 0, v18
	v_mov_b32_e32 v149, v1
	v_lshl_add_u32 v150, v7, 1, v2
	v_mov_b32_e32 v151, v1
	v_add_u32_e32 v165, 0, v20
	s_barrier
	s_branch .LBB0_486

; #define PG8_STAGE(bufoff, gbase, voff) do { _Pragma("unroll") for (int _i = 0; _i < 2; ++_i) \
;         __builtin_amdgcn_global_load_lds((const unsigned*)((const char*)(gbase) + (voff)[_i]), (PG8_LAS unsigned*)(lds + (bufoff) + ldsw + _i * 8192), 16, 0, 0); } while (0)
; #define PG8_WAIT_V(n) asm volatile("s_waitcnt vmcnt(" #n ")" ::: "memory")
; #define PG8_BAR __builtin_amdgcn_s_barrier()
; template <class Epi, class Sched, bool ALIGN_EPI = false, bool SP2 = false>
; __device__ __forceinline__ void gemm_phase(PG8_LAS unsigned char* lds, const Gemm g, const Sched& S, const Epi& E) {
;     ...
;     f32x4 acc[2][2][4][2];
; #pragma unroll
;     for (int a = 0; a < 2; ++a)
; #pragma unroll
;         for (int b = 0; b < 2; ++b)
; #pragma unroll
;             for (int m = 0; m < 4; ++m)
; #pragma unroll
;                 for (int n = 0; n < 2; ++n) acc[a][b][m][n] = (f32x4){0.f, 0.f, 0.f, 0.f};
;     bf16x8 At[4][2], B0[2][2], B1[2][2];
;     ...
;     const char* cA = (const char*)g.A + PG8_AROW(cur.pm) + (size_t)cur.ks * K * 2; const char* cB = (const char*)g.Bt + (size_t)cur.pn * tstep + (size_t)cur.ks * K * 2;
;     S.a_ready(cur);
;     if constexpr (SP2) {
;         PG8_STAGE(PG8_SB(0, 0), cB, voffB); PG8_STAGE(PG8_SB(0, 1), cB + hstep, voffB); PG8_STAGE(PG8_SA(0, 0), cA, voffA); PG8_STAGE(PG8_SA(0, 1), cA + hstep, voffA);
;         if (wr == 1) PG8_BAR;
;         PG8_WAIT_V(2); PG8_BAR;
;         PG8_STAGE(PG8_SB(1, 0), cB + kstep, voffB); PG8_STAGE(PG8_SA(1, 0), cA + kstep, voffA); PG8_STAGE(PG8_SB(1, 1), cB + hstep + kstep, voffB);
;         PG8_WAIT_V(6); PG8_BAR;
;     } else {
;         PG8_STAGE(PG8_SB(0, 0), cB, voffB); PG8_STAGE(PG8_SA(0, 0), cA, voffA); PG8_STAGE(PG8_SB(0, 1), cB + hstep, voffB); PG8_STAGE(PG8_SA(0, 1), cA + hstep, voffA);
;         if (wr == 1) PG8_BAR;
;         PG8_WAIT_V(4); PG8_BAR;
;         PG8_STAGE(PG8_SB(1, 0), cB + kstep, voffB); PG8_STAGE(PG8_SA(1, 0), cA + kstep, voffA); PG8_STAGE(PG8_SB(1, 1), cB + hstep + kstep, voffB);
;         PG8_WAIT_V(6); PG8_BAR;
;     }
.LBB0_515:
	v_bfe_u32 v195, v130, 4, 2
	v_lshl_add_u64 v[8:9], s[14:15], 0, v[0:1]
	v_mov_b32_e32 v137, v1
	v_and_b32_e32 v218, 15, v130
	v_lshlrev_b32_e32 v16, 4, v195
	v_lshlrev_b32_e32 v17, 2, v130
	v_lshl_add_u64 v[10:11], s[14:15], 0, v[136:137]
	v_mov_b32_e32 v133, v1
	s_and_b32 s26, s20, 3
	v_lshl_or_b32 v16, v218, 6, v16
	s_lshl_b32 s20, s21, 13
	v_and_b32_e32 v17, 32, v17
	s_add_i32 m0, s1, 0x18000
	v_lshl_add_u64 v[8:9], v[8:9], 0, s[56:57]
	v_lshl_add_u64 v[12:13], s[16:17], 0, v[132:133]
	v_mov_b32_e32 v135, v1
	s_lshl_b32 s0, s21, 6
	v_bitop3_b32 v18, v16, s20, v17 bitop3:0xde
	s_lshl_b32 s20, s26, 12
	global_load_lds_dwordx4 v[8:9], off
	v_lshl_add_u64 v[8:9], v[10:11], 0, s[56:57]
	s_add_i32 m0, s1, 0x1a000
	s_add_i32 s33, s1, 0x8000
	s_add_i32 s37, s1, 0xa000
	v_lshl_add_u64 v[14:15], s[16:17], 0, v[134:135]
	v_bitop3_b32 v142, v16, s20, v17 bitop3:0xde
	global_load_lds_dwordx4 v[8:9], off
	v_lshl_add_u64 v[8:9], v[12:13], 0, s[56:57]
	s_mov_b32 m0, s33
	s_add_u32 s20, s14, 0x80080
	global_load_lds_dwordx4 v[8:9], off
	v_lshl_add_u64 v[8:9], v[14:15], 0, s[56:57]
	s_mov_b32 m0, s37
	s_addc_u32 s21, s15, 0
	global_load_lds_dwordx4 v[8:9], off
	s_add_i32 m0, s1, 0x1c000
	v_lshl_add_u64 v[8:9], s[20:21], 0, v[0:1]
	global_load_lds_dwordx4 v[8:9], off
	v_lshl_add_u64 v[8:9], s[20:21], 0, v[136:137]
	s_add_i32 m0, s1, 0x1e000
	v_readlane_b32 s8, v255, 36
	global_load_lds_dwordx4 v[8:9], off
	s_waitcnt vmcnt(8)
	s_barrier
	v_lshlrev_b32_e32 v8, 15, v2
	v_and_b32_e32 v8, 0xffff0000, v8
	v_lshl_add_u32 v3, v3, 12, v8
	v_and_b32_e32 v2, 1, v2
	v_lshl_or_b32 v2, v2, 6, v3
	s_add_u32 s18, s8, s18
	v_readlane_b32 s8, v255, 37
	v_lshl_add_u32 v2, v4, 1, v2
	v_mov_b32_e32 v3, v1
	s_addc_u32 s19, s8, s19
	v_lshl_add_u64 v[138:139], s[18:19], 0, v[2:3]
	v_lshlrev_b32_e32 v2, 15, v5
	v_and_b32_e32 v2, 0xffff0000, v2
	v_lshl_add_u32 v2, v6, 12, v2
	v_and_b32_e32 v3, 1, v5
	s_waitcnt vmcnt(6)
	v_lshl_or_b32 v2, v3, 6, v2
	v_lshl_add_u32 v2, v7, 1, v2
	v_mov_b32_e32 v3, v1
	v_mov_b32_e32 v98, 0
	v_lshl_add_u64 v[140:141], s[18:19], 0, v[2:3]
	s_mov_b32 s38, -2
	s_mov_b64 s[18:19], 0
	v_add_u32_e32 v143, 0, v18
	v_mov_b32_e32 v99, v98
	v_mov_b32_e32 v100, v98
	v_mov_b32_e32 v101, v98
	v_mov_b32_e32 v102, v98
	v_mov_b32_e32 v103, v98
	v_mov_b32_e32 v104, v98
	v_mov_b32_e32 v105, v98
	v_mov_b32_e32 v118, v98
	v_mov_b32_e32 v119, v98
	v_mov_b32_e32 v120, v98
	v_mov_b32_e32 v121, v98
	v_mov_b32_e32 v114, v98
	v_mov_b32_e32 v115, v98
	v_mov_b32_e32 v116, v98
	v_mov_b32_e32 v117, v98
	v_mov_b32_e32 v70, v98
	v_mov_b32_e32 v71, v98
	v_mov_b32_e32 v72, v98
	v_mov_b32_e32 v73, v98
	v_mov_b32_e32 v66, v98
	v_mov_b32_e32 v67, v98
	v_mov_b32_e32 v68, v98
	v_mov_b32_e32 v69, v98
	v_mov_b32_e32 v86, v98
	v_mov_b32_e32 v87, v98
	v_mov_b32_e32 v88, v98
	v_mov_b32_e32 v89, v98
	v_mov_b32_e32 v82, v98
	v_mov_b32_e32 v83, v98
	v_mov_b32_e32 v84, v98
	v_mov_b32_e32 v85, v98
	v_mov_b32_e32 v110, v98
	v_mov_b32_e32 v111, v98
	v_mov_b32_e32 v112, v98
	v_mov_b32_e32 v113, v98
	v_mov_b32_e32 v106, v98
	v_mov_b32_e32 v107, v98
	v_mov_b32_e32 v108, v98
	v_mov_b32_e32 v109, v98
	v_mov_b32_e32 v126, v98
	v_mov_b32_e32 v127, v98
	v_mov_b32_e32 v128, v98
	v_mov_b32_e32 v129, v98
	v_mov_b32_e32 v122, v98
	v_mov_b32_e32 v123, v98
	v_mov_b32_e32 v124, v98
	v_mov_b32_e32 v125, v98
	v_mov_b32_e32 v78, v98
	v_mov_b32_e32 v79, v98
	v_mov_b32_e32 v80, v98
	v_mov_b32_e32 v81, v98
	v_mov_b32_e32 v74, v98
	v_mov_b32_e32 v75, v98
	v_mov_b32_e32 v76, v98
	v_mov_b32_e32 v77, v98
	v_mov_b32_e32 v94, v98
	v_mov_b32_e32 v95, v98
	v_mov_b32_e32 v96, v98
	v_mov_b32_e32 v97, v98
	v_mov_b32_e32 v90, v98
	v_mov_b32_e32 v91, v98
	v_mov_b32_e32 v92, v98
	v_mov_b32_e32 v93, v98
	v_mov_b32_e32 v6, v98
	v_mov_b32_e32 v7, v98
	v_mov_b32_e32 v8, v98
	v_mov_b32_e32 v9, v98
	v_mov_b32_e32 v2, v98
	v_mov_b32_e32 v3, v98
	v_mov_b32_e32 v4, v98
	v_mov_b32_e32 v5, v98
	v_mov_b32_e32 v22, v98
	v_mov_b32_e32 v23, v98
	v_mov_b32_e32 v24, v98
	v_mov_b32_e32 v25, v98
	v_mov_b32_e32 v18, v98
	v_mov_b32_e32 v19, v98
	v_mov_b32_e32 v20, v98
	v_mov_b32_e32 v21, v98
	v_mov_b32_e32 v38, v98
	v_mov_b32_e32 v39, v98
	v_mov_b32_e32 v40, v98
	v_mov_b32_e32 v41, v98
	v_mov_b32_e32 v34, v98
	v_mov_b32_e32 v35, v98
	v_mov_b32_e32 v36, v98
	v_mov_b32_e32 v37, v98
	v_mov_b32_e32 v54, v98
	v_mov_b32_e32 v55, v98
	v_mov_b32_e32 v56, v98
	v_mov_b32_e32 v57, v98
	v_mov_b32_e32 v50, v98
	v_mov_b32_e32 v51, v98
	v_mov_b32_e32 v52, v98
	v_mov_b32_e32 v53, v98
	v_mov_b32_e32 v14, v98
	v_mov_b32_e32 v15, v98
	v_mov_b32_e32 v16, v98
	v_mov_b32_e32 v17, v98
	v_mov_b32_e32 v10, v98
	v_mov_b32_e32 v11, v98
	v_mov_b32_e32 v12, v98
	v_mov_b32_e32 v13, v98
	v_mov_b32_e32 v30, v98
	v_mov_b32_e32 v31, v98
	v_mov_b32_e32 v32, v98
	v_mov_b32_e32 v33, v98
	v_mov_b32_e32 v26, v98
	v_mov_b32_e32 v27, v98
	v_mov_b32_e32 v28, v98
	v_mov_b32_e32 v29, v98
	v_mov_b32_e32 v46, v98
	v_mov_b32_e32 v47, v98
	v_mov_b32_e32 v48, v98
	v_mov_b32_e32 v49, v98
	v_mov_b32_e32 v42, v98
	v_mov_b32_e32 v43, v98
	v_mov_b32_e32 v44, v98
	v_mov_b32_e32 v45, v98
	v_mov_b32_e32 v62, v98
	v_mov_b32_e32 v63, v98
	v_mov_b32_e32 v64, v98
	v_mov_b32_e32 v65, v98
	v_mov_b32_e32 v58, v98
	v_mov_b32_e32 v59, v98
	v_mov_b32_e32 v60, v98
	v_mov_b32_e32 v61, v98
	s_barrier

; #define PG8_LAS __attribute__((address_space(3)))
; #define PG8_WAIT_V(n) asm volatile("s_waitcnt vmcnt(" #n ")" ::: "memory")
;     __device__ __forceinline__ void operator()(const f32x4 (&acc)[2][2][4][2], const Unit& u, int wr, int wc, int fr_in, int fq_in, PG8_LAS unsigned char* lds, int tid_in, int quad = -1) const {
;     ...
;         const int rb = u.pm * 254 - 2 > 0 ? u.pm * 254 - 2 : 0;
;         const int cl = wc * 32 + 8 * fq;
;         PG8_LAS unsigned char* HB = lds + 131072 + 4096;
;         if (fr >= 14) {
; #pragma unroll
;             for (int ai = 0; ai < 2; ++ai)
; #pragma unroll
;                 for (int m = 0; m < 4; ++m) { const f32x4 v0 = acc[ai][0][m][0], v1 = acc[ai][0][m][1];
;                     u32x4 w; w.x = cvt_pk_bf16(v0[0], v0[1]); w.y = cvt_pk_bf16(v0[2], v0[3]); w.z = cvt_pk_bf16(v1[0], v1[1]); w.w = cvt_pk_bf16(v1[2], v1[3]);
;                     *(PG8_LAS u32x4*)(HB + (((ai * 8 + wr * 4 + m) * 2 + (fr - 14)) * 128 + cl) * 2) = w; }
;         }
;         {
;             PG8_LAS float* RSw = (PG8_LAS float*)(lds + 131072);
;             const int rl_ = tid >> 1, row_ = rb + rl_;
;             const f32x4* p = (const f32x4*)(ssq + (size_t)row_ * 32 + (tid & 1) * 16);
;             const f32x4 v0 = p[0], v1 = p[1], v2 = p[2], v3 = p[3];
; template <class Epi, class Sched, bool ALIGN_EPI = false, bool SP2 = false>
; __device__ __forceinline__ void gemm_phase(PG8_LAS unsigned char* lds, const Gemm g, const Sched& S, const Epi& E) {
;     ...
;     if constexpr (SP2) {
;         PG8_STAGE(PG8_SB(0, 0), cB, voffB); PG8_STAGE(PG8_SB(0, 1), cB + hstep, voffB); PG8_STAGE(PG8_SA(0, 0), cA, voffA); PG8_STAGE(PG8_SA(0, 1), cA + hstep, voffA);
;         if (wr == 1) PG8_BAR;
;         PG8_WAIT_V(2); PG8_BAR;
;         PG8_STAGE(PG8_SB(1, 0), cB + kstep, voffB); PG8_STAGE(PG8_SA(1, 0), cA + kstep, voffA); PG8_STAGE(PG8_SB(1, 1), cB + hstep + kstep, voffB);
;         PG8_WAIT_V(6); PG8_BAR;
;     } else {
;         PG8_STAGE(PG8_SB(0, 0), cB, voffB); PG8_STAGE(PG8_SA(0, 0), cA, voffA); PG8_STAGE(PG8_SB(0, 1), cB + hstep, voffB); PG8_STAGE(PG8_SA(0, 1), cA + hstep, voffA);
;         if (wr == 1) PG8_BAR;
;         PG8_WAIT_V(4); PG8_BAR;
;         PG8_STAGE(PG8_SB(1, 0), cB + kstep, voffB); PG8_STAGE(PG8_SA(1, 0), cA + kstep, voffA); PG8_STAGE(PG8_SB(1, 1), cB + hstep + kstep, voffB);
;         PG8_WAIT_V(6); PG8_BAR;
;     }
.LBB0_631:
	v_readlane_b32 s8, v253, 57
	v_readlane_b32 s60, v255, 60
	s_mul_i32 s14, s8, 0x10800
	v_readlane_b32 s66, v253, 2
	s_mul_hi_u32 s11, s8, 0x10800
	v_readlane_b32 s61, v255, 61
	v_readlane_b32 s67, v253, 3
	s_add_u32 s60, s66, s14
	s_addc_u32 s61, s67, s11
	s_lshl_b32 s3, s3, 5
	v_readlane_b32 s72, v253, 8
	s_and_b32 s89, s3, 0x60
	s_add_i32 m0, s77, 0x18000
	v_lshl_add_u64 v[6:7], v[6:7], 0, s[56:57]
	s_lshl_b32 s72, s10, 6
	s_lshl_b32 s11, s10, 13
	s_lshl_b32 s3, s89, 7
	global_load_lds_dwordx4 v[6:7], off
	v_lshl_add_u64 v[4:5], v[4:5], 0, s[56:57]
	s_add_i32 m0, s77, 0x1a000
	s_add_i32 s88, s77, 0x8000
	s_add_i32 s37, s77, 0xa000
	global_load_lds_dwordx4 v[4:5], off
	v_lshl_add_u64 v[2:3], v[2:3], 0, s[56:57]
	s_mov_b32 m0, s88
	s_add_u32 s14, s48, 0x80080
	global_load_lds_dwordx4 v[2:3], off
	v_lshl_add_u64 v[2:3], v[8:9], 0, s[56:57]
	s_mov_b32 m0, s37
	s_addc_u32 s15, s49, 0
	global_load_lds_dwordx4 v[2:3], off
	s_add_i32 m0, s77, 0x1c000
	v_lshl_add_u64 v[2:3], s[14:15], 0, v[158:159]
	global_load_lds_dwordx4 v[2:3], off
	v_lshl_add_u64 v[2:3], s[14:15], 0, v[162:163]
	s_add_i32 m0, s77, 0x1e000
	v_readlane_b32 s68, v253, 4
	global_load_lds_dwordx4 v[2:3], off
	s_waitcnt vmcnt(8)
	s_barrier
	v_readlane_b32 s69, v253, 5
	s_cmpk_lt_u32 s2, 0x100
	s_cselect_b64 s[68:69], -1, 0
	s_lshl_b32 s2, s10, 11
	s_add_i32 s2, s2, 0
	s_add_i32 s2, s2, 0x21000
	s_lshl_b32 s55, s10, 10
	v_readlane_b32 s70, v253, 6
	v_readlane_b32 s71, v253, 7
	s_cmp_gt_i32 s10, 0
	s_cselect_b64 s[70:71], -1, 0
	s_cmp_gt_i32 s10, -1
	s_cselect_b64 s[58:59], -1, 0
	s_or_b32 s33, s55, 0x100
	s_or_b32 s94, s55, 0x200
	s_or_b32 s95, s55, 0x300
	v_lshlrev_b32_e32 v2, 15, v0
	v_readlane_b32 s62, v255, 62
	s_waitcnt vmcnt(0)
	v_bfe_u32 v191, v185, 4, 2
	s_cmp_gt_i32 s10, -2
	v_and_b32_e32 v2, 0xffff0000, v2
	v_and_b32_e32 v190, 15, v185
	v_lshlrev_b32_e32 v15, 4, v191
	v_lshlrev_b32_e32 v16, 2, v185
	s_cselect_b64 s[38:39], -1, 0
	s_add_i32 s62, s55, 0x800
	v_lshl_add_u32 v2, v10, 12, v2
	v_and_b32_e32 v0, 1, v0
	v_readlane_b32 s63, v255, 63
	v_lshl_or_b32 v15, v190, 6, v15
	v_and_b32_e32 v16, 32, v16
	s_cmp_gt_i32 s10, -3
	v_lshl_or_b32 v0, v0, 6, v2
	v_bitop3_b32 v17, v15, s11, v16 bitop3:0xde
	s_cselect_b64 s[40:41], -1, 0
	s_add_i32 s63, s55, 0x900
	s_add_i32 s10, s55, 0xa00
	s_add_i32 s11, s55, 0xb00
	v_lshl_add_u32 v164, v11, 1, v0
	v_lshlrev_b32_e32 v0, 15, v12
	s_add_u32 s14, s60, 0x5800
	v_and_b32_e32 v0, 0xffff0000, v0
	s_waitcnt vmcnt(6)
	s_addc_u32 s15, s61, 0
	v_lshl_add_u32 v0, v13, 12, v0
	v_and_b32_e32 v2, 1, v12
	v_readlane_b32 s64, v253, 0
	v_readlane_b32 s65, v253, 1
	v_readlane_b32 s75, v253, 11
	s_add_u32 s16, s60, 0xb000
	v_lshl_or_b32 v0, v2, 6, v0
	v_readlane_b32 s66, v253, 28
	v_bitop3_b32 v192, v15, s3, v16 bitop3:0xde
	s_mov_b32 s3, 0
	s_addc_u32 s17, s61, 0
	v_mov_b32_e32 v165, v1
	v_lshl_add_u32 v166, v14, 1, v0
	v_mov_b32_e32 v167, v1
	v_add_u32_e32 v193, 0, v17
	s_mov_b32 s64, s19
	s_mov_b32 s65, s20
	v_readlane_b32 s67, v253, 29
	s_movk_i32 s75, 0x140
	v_readlane_b32 s73, v253, 9
	v_readlane_b32 s74, v253, 10
	s_barrier
	s_branch .LBB0_634

; #define PG8_STAGE(bufoff, gbase, voff) do { _Pragma("unroll") for (int _i = 0; _i < 2; ++_i) \
;         __builtin_amdgcn_global_load_lds((const unsigned*)((const char*)(gbase) + (voff)[_i]), (PG8_LAS unsigned*)(lds + (bufoff) + ldsw + _i * 8192), 16, 0, 0); } while (0)
; #define PG8_WAIT_V(n) asm volatile("s_waitcnt vmcnt(" #n ")" ::: "memory")
; #define PG8_BAR __builtin_amdgcn_s_barrier()
; template <class Epi, class Sched, bool ALIGN_EPI = false, bool SP2 = false>
; __device__ __forceinline__ void gemm_phase(PG8_LAS unsigned char* lds, const Gemm g, const Sched& S, const Epi& E) {
;     ...
;     for (int i = 0; i < 2; ++i) { int R, C; stage_rc(tid * 16 + i * 8192, R, C); const int Rb = Epi::PERM ? ((R & ~31) + perm32(R & 31)) : R;
;         voffA[i] = (unsigned)(R * g.ld + C) * 2u; voffB[i] = (unsigned)(Rb * g.ld + C) * 2u; }
;     ...
;     if constexpr (SP2) {
;         PG8_STAGE(PG8_SB(0, 0), cB, voffB); PG8_STAGE(PG8_SB(0, 1), cB + hstep, voffB); PG8_STAGE(PG8_SA(0, 0), cA, voffA); PG8_STAGE(PG8_SA(0, 1), cA + hstep, voffA);
;         if (wr == 1) PG8_BAR;
;         PG8_WAIT_V(2); PG8_BAR;
;         PG8_STAGE(PG8_SB(1, 0), cB + kstep, voffB); PG8_STAGE(PG8_SA(1, 0), cA + kstep, voffA); PG8_STAGE(PG8_SB(1, 1), cB + hstep + kstep, voffB);
;         PG8_WAIT_V(6); PG8_BAR;
;     } else {
;         PG8_STAGE(PG8_SB(0, 0), cB, voffB); PG8_STAGE(PG8_SA(0, 0), cA, voffA); PG8_STAGE(PG8_SB(0, 1), cB + hstep, voffB); PG8_STAGE(PG8_SA(0, 1), cA + hstep, voffA);
;         if (wr == 1) PG8_BAR;
;         PG8_WAIT_V(4); PG8_BAR;
;         PG8_STAGE(PG8_SB(1, 0), cB + kstep, voffB); PG8_STAGE(PG8_SA(1, 0), cA + kstep, voffA); PG8_STAGE(PG8_SB(1, 1), cB + hstep + kstep, voffB);
;         PG8_WAIT_V(6); PG8_BAR;
;     }
.LBB0_990:
	v_bfe_u32 v19, v18, 4, 2
	v_and_b32_e32 v20, 15, v18
	v_lshlrev_b32_e32 v22, 4, v19
	v_lshlrev_b32_e32 v18, 2, v18
	s_and_b32 s33, s17, 3
	v_lshl_or_b32 v162, s18, 6, v20
	v_lshl_or_b32 v20, v20, 6, v22
	s_lshl_b32 s17, s18, 13
	v_and_b32_e32 v18, 32, v18
	s_add_i32 m0, s2, 0x18000
	v_lshl_add_u64 v[8:9], v[8:9], 0, s[56:57]
	v_bitop3_b32 v22, v20, s17, v18 bitop3:0xde
	s_lshl_b32 s17, s33, 12
	global_load_lds_dwordx4 v[8:9], off
	v_lshl_add_u64 v[6:7], v[6:7], 0, s[56:57]
	s_add_i32 m0, s2, 0x1a000
	s_add_i32 s37, s2, 0x8000
	s_add_i32 s46, s2, 0xa000
	global_load_lds_dwordx4 v[6:7], off
	v_lshl_add_u64 v[2:3], v[2:3], 0, s[56:57]
	s_mov_b32 m0, s37
	s_add_u32 s18, s24, 0x160080
	global_load_lds_dwordx4 v[2:3], off
	v_lshl_add_u64 v[2:3], v[4:5], 0, s[56:57]
	s_mov_b32 m0, s46
	s_addc_u32 s19, s25, 0
	global_load_lds_dwordx4 v[2:3], off
	s_add_i32 m0, s2, 0x1c000
	v_lshl_add_u64 v[2:3], s[18:19], 0, v[0:1]
	global_load_lds_dwordx4 v[2:3], off
	v_lshl_add_u64 v[2:3], s[18:19], 0, v[146:147]
	s_add_i32 m0, s2, 0x1e000
	s_movk_i32 s20, 0x1600
	global_load_lds_dwordx4 v[2:3], off
	s_waitcnt vmcnt(8)
	s_barrier
	v_lshrrev_b32_e32 v3, 1, v10
	v_mul_lo_u32 v2, v12, s20
	s_mov_b32 s8, 0x16000
	v_mad_u64_u32 v[2:3], s[18:19], v3, s8, v[2:3]
	v_or_b32_e32 v2, v2, v11
	v_add_lshl_u32 v2, v2, v13, 1
	v_mov_b32_e32 v3, v1
	s_mov_b64 s[40:41], 0x160080
	v_lshl_add_u64 v[148:149], v[2:3], 0, s[40:41]
	v_lshrrev_b32_e32 v3, 1, v14
	v_mul_lo_u32 v2, v16, s20
	v_mad_u64_u32 v[2:3], s[18:19], v3, s8, v[2:3]
	s_waitcnt vmcnt(6)
	v_or_b32_e32 v2, v2, v15
	v_lshlrev_b32_e32 v21, 3, v19
	s_cmpk_lt_u32 s16, 0x100
	v_add_lshl_u32 v2, v2, v17, 1
	v_mov_b32_e32 v3, v1
	v_bitop3_b32 v163, v20, s17, v18 bitop3:0xde
	v_lshl_or_b32 v164, s33, 5, v21
	s_cselect_b64 s[16:17], -1, 0
	s_mov_b32 s47, 0
	v_cmp_eq_u32_e64 s[38:39], 0, v19
	v_lshl_add_u64 v[150:151], v[2:3], 0, s[40:41]
	v_add_u32_e32 v165, 0, v22
	s_barrier
	s_branch .LBB0_993

; #define PG8_STAGE(bufoff, gbase, voff) do { _Pragma("unroll") for (int _i = 0; _i < 2; ++_i) \
;         __builtin_amdgcn_global_load_lds((const unsigned*)((const char*)(gbase) + (voff)[_i]), (PG8_LAS unsigned*)(lds + (bufoff) + ldsw + _i * 8192), 16, 0, 0); } while (0)
; #define PG8_WAIT_V(n) asm volatile("s_waitcnt vmcnt(" #n ")" ::: "memory")
; #define PG8_BAR __builtin_amdgcn_s_barrier()
; template <class Epi, class Sched, bool ALIGN_EPI = false, bool SP2 = false>
; __device__ __forceinline__ void gemm_phase(PG8_LAS unsigned char* lds, const Gemm g, const Sched& S, const Epi& E) {
;     ...
;     f32x4 acc[2][2][4][2];
; #pragma unroll
;     for (int a = 0; a < 2; ++a)
; #pragma unroll
;         for (int b = 0; b < 2; ++b)
; #pragma unroll
;             for (int m = 0; m < 4; ++m)
; #pragma unroll
;                 for (int n = 0; n < 2; ++n) acc[a][b][m][n] = (f32x4){0.f, 0.f, 0.f, 0.f};
;     bf16x8 At[4][2], B0[2][2], B1[2][2];
;     ...
;     const char* cA = (const char*)g.A + PG8_AROW(cur.pm) + (size_t)cur.ks * K * 2; const char* cB = (const char*)g.Bt + (size_t)cur.pn * tstep + (size_t)cur.ks * K * 2;
;     S.a_ready(cur);
;     if constexpr (SP2) {
;         PG8_STAGE(PG8_SB(0, 0), cB, voffB); PG8_STAGE(PG8_SB(0, 1), cB + hstep, voffB); PG8_STAGE(PG8_SA(0, 0), cA, voffA); PG8_STAGE(PG8_SA(0, 1), cA + hstep, voffA);
;         if (wr == 1) PG8_BAR;
;         PG8_WAIT_V(2); PG8_BAR;
;         PG8_STAGE(PG8_SB(1, 0), cB + kstep, voffB); PG8_STAGE(PG8_SA(1, 0), cA + kstep, voffA); PG8_STAGE(PG8_SB(1, 1), cB + hstep + kstep, voffB);
;         PG8_WAIT_V(6); PG8_BAR;
;     } else {
;         PG8_STAGE(PG8_SB(0, 0), cB, voffB); PG8_STAGE(PG8_SA(0, 0), cA, voffA); PG8_STAGE(PG8_SB(0, 1), cB + hstep, voffB); PG8_STAGE(PG8_SA(0, 1), cA + hstep, voffA);
;         if (wr == 1) PG8_BAR;
;         PG8_WAIT_V(4); PG8_BAR;
;         PG8_STAGE(PG8_SB(1, 0), cB + kstep, voffB); PG8_STAGE(PG8_SA(1, 0), cA + kstep, voffA); PG8_STAGE(PG8_SB(1, 1), cB + hstep + kstep, voffB);
;         PG8_WAIT_V(6); PG8_BAR;
;     }
.LBB0_1026:
	v_bfe_u32 v195, v130, 4, 2
	v_and_b32_e32 v217, 15, v130
	v_lshlrev_b32_e32 v18, 4, v195
	v_lshlrev_b32_e32 v19, 2, v130
	s_and_b32 s26, s0, 3
	s_lshl_b32 s0, s20, 6
	v_lshl_or_b32 v18, v217, 6, v18
	s_lshl_b32 s20, s20, 13
	v_and_b32_e32 v19, 32, v19
	s_add_i32 m0, s3, 0x18000
	v_lshl_add_u64 v[8:9], v[8:9], 0, s[56:57]
	v_bitop3_b32 v20, v18, s20, v19 bitop3:0xde
	s_lshl_b32 s20, s26, 12
	global_load_lds_dwordx4 v[8:9], off
	v_lshl_add_u64 v[6:7], v[6:7], 0, s[56:57]
	s_add_i32 m0, s3, 0x1a000
	s_add_i32 s33, s3, 0x8000
	s_add_i32 s37, s3, 0xa000
	v_bitop3_b32 v142, v18, s20, v19 bitop3:0xde
	global_load_lds_dwordx4 v[6:7], off
	v_lshl_add_u64 v[4:5], v[4:5], 0, s[56:57]
	s_mov_b32 m0, s33
	s_add_u32 s20, s14, 0x160080
	global_load_lds_dwordx4 v[4:5], off
	v_lshl_add_u64 v[2:3], v[2:3], 0, s[56:57]
	s_mov_b32 m0, s37
	s_addc_u32 s21, s15, 0
	global_load_lds_dwordx4 v[2:3], off
	s_add_i32 m0, s3, 0x1c000
	v_lshl_add_u64 v[2:3], s[20:21], 0, v[0:1]
	global_load_lds_dwordx4 v[2:3], off
	v_lshl_add_u64 v[2:3], s[20:21], 0, v[136:137]
	s_add_i32 m0, s3, 0x1e000
	s_movk_i32 s23, 0x1600
	global_load_lds_dwordx4 v[2:3], off
	s_waitcnt vmcnt(8)
	s_barrier
	v_lshrrev_b32_e32 v3, 1, v10
	v_mul_lo_u32 v2, v12, s23
	s_mov_b32 s22, 0x16000
	v_mad_u64_u32 v[2:3], s[20:21], v3, s22, v[2:3]
	v_readlane_b32 s8, v253, 12
	v_or_b32_e32 v2, v2, v11
	s_add_u32 s20, s8, s19
	v_readlane_b32 s8, v253, 13
	v_add_lshl_u32 v2, v2, v13, 1
	v_mov_b32_e32 v3, v1
	s_addc_u32 s21, s8, s18
	v_lshl_add_u64 v[138:139], s[20:21], 0, v[2:3]
	v_lshrrev_b32_e32 v3, 1, v14
	v_mul_lo_u32 v2, v16, s23
	v_mad_u64_u32 v[2:3], s[18:19], v3, s22, v[2:3]
	s_waitcnt vmcnt(6)
	v_or_b32_e32 v2, v2, v15
	v_add_lshl_u32 v2, v2, v17, 1
	v_mov_b32_e32 v3, v1
	v_mov_b32_e32 v98, 0
	v_lshl_add_u64 v[140:141], s[20:21], 0, v[2:3]
	s_mov_b32 s38, -2
	s_mov_b64 s[18:19], 0
	v_add_u32_e32 v143, 0, v20
	v_mov_b32_e32 v99, v98
	v_mov_b32_e32 v100, v98
	v_mov_b32_e32 v101, v98
	v_mov_b32_e32 v102, v98
	v_mov_b32_e32 v103, v98
	v_mov_b32_e32 v104, v98
	v_mov_b32_e32 v105, v98
	v_mov_b32_e32 v118, v98
	v_mov_b32_e32 v119, v98
	v_mov_b32_e32 v120, v98
	v_mov_b32_e32 v121, v98
	v_mov_b32_e32 v114, v98
	v_mov_b32_e32 v115, v98
	v_mov_b32_e32 v116, v98
	v_mov_b32_e32 v117, v98
	v_mov_b32_e32 v70, v98
	v_mov_b32_e32 v71, v98
	v_mov_b32_e32 v72, v98
	v_mov_b32_e32 v73, v98
	v_mov_b32_e32 v66, v98
	v_mov_b32_e32 v67, v98
	v_mov_b32_e32 v68, v98
	v_mov_b32_e32 v69, v98
	v_mov_b32_e32 v86, v98
	v_mov_b32_e32 v87, v98
	v_mov_b32_e32 v88, v98
	v_mov_b32_e32 v89, v98
	v_mov_b32_e32 v82, v98
	v_mov_b32_e32 v83, v98
	v_mov_b32_e32 v84, v98
	v_mov_b32_e32 v85, v98
	v_mov_b32_e32 v110, v98
	v_mov_b32_e32 v111, v98
	v_mov_b32_e32 v112, v98
	v_mov_b32_e32 v113, v98
	v_mov_b32_e32 v106, v98
	v_mov_b32_e32 v107, v98
	v_mov_b32_e32 v108, v98
	v_mov_b32_e32 v109, v98
	v_mov_b32_e32 v126, v98
	v_mov_b32_e32 v127, v98
	v_mov_b32_e32 v128, v98
	v_mov_b32_e32 v129, v98
	v_mov_b32_e32 v122, v98
	v_mov_b32_e32 v123, v98
	v_mov_b32_e32 v124, v98
	v_mov_b32_e32 v125, v98
	v_mov_b32_e32 v78, v98
	v_mov_b32_e32 v79, v98
	v_mov_b32_e32 v80, v98
	v_mov_b32_e32 v81, v98
	v_mov_b32_e32 v74, v98
	v_mov_b32_e32 v75, v98
	v_mov_b32_e32 v76, v98
	v_mov_b32_e32 v77, v98
	v_mov_b32_e32 v94, v98
	v_mov_b32_e32 v95, v98
	v_mov_b32_e32 v96, v98
	v_mov_b32_e32 v97, v98
	v_mov_b32_e32 v90, v98
	v_mov_b32_e32 v91, v98
	v_mov_b32_e32 v92, v98
	v_mov_b32_e32 v93, v98
	v_mov_b32_e32 v6, v98
	v_mov_b32_e32 v7, v98
	v_mov_b32_e32 v8, v98
	v_mov_b32_e32 v9, v98
	v_mov_b32_e32 v2, v98
	v_mov_b32_e32 v3, v98
	v_mov_b32_e32 v4, v98
	v_mov_b32_e32 v5, v98
	v_mov_b32_e32 v22, v98
	v_mov_b32_e32 v23, v98
	v_mov_b32_e32 v24, v98
	v_mov_b32_e32 v25, v98
	v_mov_b32_e32 v18, v98
	v_mov_b32_e32 v19, v98
	v_mov_b32_e32 v20, v98
	v_mov_b32_e32 v21, v98
	v_mov_b32_e32 v38, v98
	v_mov_b32_e32 v39, v98
	v_mov_b32_e32 v40, v98
	v_mov_b32_e32 v41, v98
	v_mov_b32_e32 v34, v98
	v_mov_b32_e32 v35, v98
	v_mov_b32_e32 v36, v98
	v_mov_b32_e32 v37, v98
	v_mov_b32_e32 v54, v98
	v_mov_b32_e32 v55, v98
	v_mov_b32_e32 v56, v98
	v_mov_b32_e32 v57, v98
	v_mov_b32_e32 v50, v98
	v_mov_b32_e32 v51, v98
	v_mov_b32_e32 v52, v98
	v_mov_b32_e32 v53, v98
	v_mov_b32_e32 v14, v98
	v_mov_b32_e32 v15, v98
	v_mov_b32_e32 v16, v98
	v_mov_b32_e32 v17, v98
	v_mov_b32_e32 v10, v98
	v_mov_b32_e32 v11, v98
	v_mov_b32_e32 v12, v98
	v_mov_b32_e32 v13, v98
	v_mov_b32_e32 v30, v98
	v_mov_b32_e32 v31, v98
	v_mov_b32_e32 v32, v98
	v_mov_b32_e32 v33, v98
	v_mov_b32_e32 v26, v98
	v_mov_b32_e32 v27, v98
	v_mov_b32_e32 v28, v98
	v_mov_b32_e32 v29, v98
	v_mov_b32_e32 v46, v98
	v_mov_b32_e32 v47, v98
	v_mov_b32_e32 v48, v98
	v_mov_b32_e32 v49, v98
	v_mov_b32_e32 v42, v98
	v_mov_b32_e32 v43, v98
	v_mov_b32_e32 v44, v98
	v_mov_b32_e32 v45, v98
	v_mov_b32_e32 v62, v98
	v_mov_b32_e32 v63, v98
	v_mov_b32_e32 v64, v98
	v_mov_b32_e32 v65, v98
	v_mov_b32_e32 v58, v98
	v_mov_b32_e32 v59, v98
	v_mov_b32_e32 v60, v98
	v_mov_b32_e32 v61, v98
	s_barrier
